# gemm1 tail half tiles + batched tail convert, with hot loops kept at their previous 8-byte placement phase
# speedup vs baseline: 1.0036x; 1.0036x over previous
.LBB0_215:
	s_mul_i32 s7, s60, s80
	v_readlane_b32 s0, v254, 54
	s_mul_hi_u32 s6, s60, s80
	s_add_u32 s8, s7, s0
	s_addc_u32 s9, s6, 0
	s_mov_b32 s100, 0
	s_mov_b32 s101, 0
	s_cmp_lg_u32 s7, 0x400
	s_cbranch_scc1 .Lg1_full
.Lg1_r4:
	s_cmp_gt_u32 s0, 63
	s_cbranch_scc1 .Lg1_full
	s_lshr_b32 s100, s0, 5
	s_lshl_b32 s100, s100, 7
	s_mov_b32 s101, 1
	s_and_b32 s8, s0, 31
	s_add_u32 s8, s8, 0x400
	s_mov_b32 s9, 0

.LBB0_224:
	s_or_b64 exec, exec, s[6:7]
	s_add_i32 s37, s27, 0x18000
	s_or_b32 s6, s9, 0x80
	s_mov_b32 m0, s37
	s_add_i32 s38, s27, 0x1a000
	s_waitcnt vmcnt(4)
	s_barrier
	buffer_load_dwordx4 v140, s[44:47], s6 offen lds
	s_mov_b32 m0, s38
	s_add_i32 s39, s27, 0x8000
	buffer_load_dwordx4 v141, s[44:47], s6 offen lds
	s_or_b32 s6, s8, 0x80
	s_mov_b32 m0, s39
	s_add_i32 s62, s27, 0xa000
	buffer_load_dwordx4 v140, s[48:51], s6 offen lds
	s_mov_b32 m0, s62
	s_add_i32 s63, s27, 0x1c000
	buffer_load_dwordx4 v141, s[48:51], s6 offen lds
	s_or_b32 s6, s9, 0x80080
	s_mov_b32 m0, s63
	s_add_i32 s66, s27, 0x1e000
	buffer_load_dwordx4 v140, s[44:47], s6 offen lds
	s_mov_b32 m0, s66
	v_mov_b32_e32 v0, 0
	buffer_load_dwordx4 v141, s[44:47], s6 offen lds
	s_waitcnt vmcnt(6)
	s_add_i32 s7, s27, 0xc000
	s_add_i32 s6, s27, 0xe000
	s_mov_b32 s67, -2
	s_mov_b32 s68, 0
	v_mov_b32_e32 v1, v0
	v_mov_b32_e32 v2, v0
	v_mov_b32_e32 v3, v0
	v_mov_b32_e32 v4, v0
	v_mov_b32_e32 v5, v0
	v_mov_b32_e32 v6, v0
	v_mov_b32_e32 v7, v0
	v_mov_b32_e32 v8, v0
	v_mov_b32_e32 v9, v0
	v_mov_b32_e32 v10, v0
	v_mov_b32_e32 v11, v0
	v_mov_b32_e32 v12, v0
	v_mov_b32_e32 v13, v0
	v_mov_b32_e32 v14, v0
	v_mov_b32_e32 v15, v0
	v_mov_b32_e32 v18, v0
	v_mov_b32_e32 v19, v0
	v_mov_b32_e32 v20, v0
	v_mov_b32_e32 v21, v0
	v_mov_b32_e32 v22, v0
	v_mov_b32_e32 v23, v0
	v_mov_b32_e32 v24, v0
	v_mov_b32_e32 v25, v0
	v_mov_b32_e32 v26, v0
	v_mov_b32_e32 v27, v0
	v_mov_b32_e32 v28, v0
	v_mov_b32_e32 v29, v0
	v_mov_b32_e32 v30, v0
	v_mov_b32_e32 v31, v0
	v_mov_b32_e32 v32, v0
	v_mov_b32_e32 v33, v0
	v_mov_b32_e32 v34, v0
	v_mov_b32_e32 v35, v0
	v_mov_b32_e32 v36, v0
	v_mov_b32_e32 v37, v0
	v_mov_b32_e32 v38, v0
	v_mov_b32_e32 v39, v0
	v_mov_b32_e32 v40, v0
	v_mov_b32_e32 v41, v0
	v_mov_b32_e32 v42, v0
	v_mov_b32_e32 v43, v0
	v_mov_b32_e32 v44, v0
	v_mov_b32_e32 v45, v0
	v_mov_b32_e32 v46, v0
	v_mov_b32_e32 v47, v0
	v_mov_b32_e32 v48, v0
	v_mov_b32_e32 v49, v0
	v_mov_b32_e32 v50, v0
	v_mov_b32_e32 v51, v0
	v_mov_b32_e32 v52, v0
	v_mov_b32_e32 v53, v0
	v_mov_b32_e32 v54, v0
	v_mov_b32_e32 v55, v0
	v_mov_b32_e32 v56, v0
	v_mov_b32_e32 v57, v0
	v_mov_b32_e32 v58, v0
	v_mov_b32_e32 v59, v0
	v_mov_b32_e32 v60, v0
	v_mov_b32_e32 v61, v0
	v_mov_b32_e32 v62, v0
	v_mov_b32_e32 v63, v0
	v_mov_b32_e32 v64, v0
	v_mov_b32_e32 v65, v0
	v_mov_b32_e32 v66, v0
	v_mov_b32_e32 v67, v0
	v_mov_b32_e32 v68, v0
	v_mov_b32_e32 v69, v0
	v_mov_b32_e32 v70, v0
	v_mov_b32_e32 v71, v0
	v_mov_b32_e32 v72, v0
	v_mov_b32_e32 v73, v0
	v_mov_b32_e32 v74, v0
	v_mov_b32_e32 v75, v0
	v_mov_b32_e32 v76, v0
	v_mov_b32_e32 v77, v0
	v_mov_b32_e32 v78, v0
	v_mov_b32_e32 v79, v0
	v_mov_b32_e32 v80, v0
	v_mov_b32_e32 v81, v0
	v_mov_b32_e32 v82, v0
	v_mov_b32_e32 v83, v0
	v_mov_b32_e32 v84, v0
	v_mov_b32_e32 v85, v0
	v_mov_b32_e32 v86, v0
	v_mov_b32_e32 v87, v0
	v_mov_b32_e32 v88, v0
	v_mov_b32_e32 v89, v0
	v_mov_b32_e32 v90, v0
	v_mov_b32_e32 v91, v0
	v_mov_b32_e32 v92, v0
	v_mov_b32_e32 v93, v0
	v_mov_b32_e32 v94, v0
	v_mov_b32_e32 v95, v0
	v_mov_b32_e32 v96, v0
	v_mov_b32_e32 v97, v0
	v_mov_b32_e32 v98, v0
	v_mov_b32_e32 v99, v0
	v_mov_b32_e32 v100, v0
	v_mov_b32_e32 v101, v0
	v_mov_b32_e32 v102, v0
	v_mov_b32_e32 v103, v0
	v_mov_b32_e32 v104, v0
	v_mov_b32_e32 v105, v0
	v_mov_b32_e32 v106, v0
	v_mov_b32_e32 v107, v0
	v_mov_b32_e32 v108, v0
	v_mov_b32_e32 v109, v0
	v_mov_b32_e32 v110, v0
	v_mov_b32_e32 v111, v0
	v_mov_b32_e32 v112, v0
	v_mov_b32_e32 v113, v0
	v_mov_b32_e32 v114, v0
	v_mov_b32_e32 v115, v0
	v_mov_b32_e32 v116, v0
	v_mov_b32_e32 v117, v0
	v_mov_b32_e32 v118, v0
	v_mov_b32_e32 v119, v0
	v_mov_b32_e32 v120, v0
	v_mov_b32_e32 v121, v0
	v_mov_b32_e32 v122, v0
	v_mov_b32_e32 v123, v0
	v_mov_b32_e32 v124, v0
	v_mov_b32_e32 v125, v0
	v_mov_b32_e32 v126, v0
	v_mov_b32_e32 v127, v0
	v_mov_b32_e32 v128, v0
	v_mov_b32_e32 v129, v0
	s_nop 0
	s_barrier

.Lg1_sk3:
	s_setprio 0
	s_add_i32 s67, s67, 2
	s_addk_i32 s68, 0x100
	s_cmp_lt_u32 s67, 28
	s_barrier
	s_cbranch_scc1 .LBB0_225
	s_nop 0
	v_mov_b32_e32 v150, v130
	s_or_b32 s8, s8, 0x80f80
	v_and_b32_e32 v158, 15, v150
	v_bfe_u32 v132, v150, 4, 2
	v_lshlrev_b32_e32 v134, 2, v150
	v_bfe_u32 v152, v150, 6, 2
	v_lshlrev_b32_e32 v151, 4, v132
	v_lshlrev_b32_e32 v133, 6, v158
	v_and_b32_e32 v139, 32, v134
	v_lshlrev_b32_e32 v138, 12, v152
	v_bitop3_b32 v153, v151, v139, v133 bitop3:0x36
	v_add3_u32 v133, s78, v153, v138
	ds_read_b128 v[134:137], v133
	ds_read_b128 v[154:157], v133 offset:1024
	ds_read_b128 v[160:163], v133 offset:2048
	ds_read_b128 v[164:167], v133 offset:3072
	v_ashrrev_i32_e32 v133, 2, v150
	v_lshlrev_b32_e32 v172, 6, v150
	v_and_b32_e32 v133, 0xffffffc0, v133
	v_and_b32_e32 v172, 0x3c0, v172
	v_lshlrev_b32_e32 v159, 7, v133
	v_bitop3_b32 v139, v172, v139, v151 bitop3:0x36
	s_waitcnt vmcnt(0)
	v_add3_u32 v176, 0, v153, v159
	v_add3_u32 v139, 0, v139, v159
	s_mov_b32 m0, s7
	ds_read_b128 v[168:171], v176
	ds_read_b128 v[178:181], v176 offset:1024
	ds_read_b128 v[214:217], v139 offset:2048
	ds_read_b128 v[218:221], v139 offset:3072
	ds_read_b128 v[222:225], v139 offset:4096
	ds_read_b128 v[226:229], v139 offset:5120
	ds_read_b128 v[230:233], v139 offset:6144
	ds_read_b128 v[234:237], v139 offset:7168
	buffer_load_dwordx4 v140, s[48:51], s8 offen lds
	s_mov_b32 m0, s6
	s_nop 0
	buffer_load_dwordx4 v141, s[48:51], s8 offen lds
	s_barrier
	s_waitcnt lgkmcnt(0)
	s_setprio 1
	s_waitcnt lgkmcnt(0)
	v_mfma_f32_16x16x32_bf16 v[126:129], v[134:137], v[168:171], v[126:129]
	v_mfma_f32_16x16x32_bf16 v[122:125], v[160:163], v[168:171], v[122:125]
	v_mfma_f32_16x16x32_bf16 v[118:121], v[134:137], v[214:217], v[118:121]
	v_mfma_f32_16x16x32_bf16 v[114:117], v[160:163], v[214:217], v[114:117]
	v_mfma_f32_16x16x32_bf16 v[110:113], v[134:137], v[222:225], v[110:113]
	v_mfma_f32_16x16x32_bf16 v[106:109], v[160:163], v[222:225], v[106:109]
	v_mfma_f32_16x16x32_bf16 v[102:105], v[134:137], v[230:233], v[102:105]
	v_mfma_f32_16x16x32_bf16 v[98:101], v[160:163], v[230:233], v[98:101]
	v_mfma_f32_16x16x32_bf16 v[126:129], v[154:157], v[178:181], v[126:129]
	v_mfma_f32_16x16x32_bf16 v[122:125], v[164:167], v[178:181], v[122:125]
	v_mfma_f32_16x16x32_bf16 v[118:121], v[154:157], v[218:221], v[118:121]
	v_mfma_f32_16x16x32_bf16 v[114:117], v[164:167], v[218:221], v[114:117]
	v_mfma_f32_16x16x32_bf16 v[110:113], v[154:157], v[226:229], v[110:113]
	v_mfma_f32_16x16x32_bf16 v[106:109], v[164:167], v[226:229], v[106:109]
	v_mfma_f32_16x16x32_bf16 v[102:105], v[154:157], v[234:237], v[102:105]
	v_mfma_f32_16x16x32_bf16 v[98:101], v[164:167], v[234:237], v[98:101]
	s_setprio 0
	v_add3_u32 v159, s77, v153, v138
	s_barrier
	ds_read_b128 v[238:241], v159
	ds_read_b128 v[242:245], v159 offset:1024
	ds_read_b128 v[246:249], v159 offset:2048
	ds_read_b128 v[250:253], v159 offset:3072
	s_barrier
	s_waitcnt lgkmcnt(0)
	s_setprio 1
	s_waitcnt lgkmcnt(0)
	v_mfma_f32_16x16x32_bf16 v[94:97], v[238:241], v[168:171], v[94:97]
	v_mfma_f32_16x16x32_bf16 v[182:185], v[242:245], v[178:181], v[94:97]
	v_mfma_f32_16x16x32_bf16 v[90:93], v[246:249], v[168:171], v[90:93]
	v_mfma_f32_16x16x32_bf16 v[86:89], v[238:241], v[214:217], v[86:89]
	v_mfma_f32_16x16x32_bf16 v[82:85], v[246:249], v[214:217], v[82:85]
	v_mfma_f32_16x16x32_bf16 v[78:81], v[238:241], v[222:225], v[78:81]
	v_mfma_f32_16x16x32_bf16 v[74:77], v[246:249], v[222:225], v[74:77]
	v_mfma_f32_16x16x32_bf16 v[70:73], v[238:241], v[230:233], v[70:73]
	v_mfma_f32_16x16x32_bf16 v[66:69], v[246:249], v[230:233], v[66:69]
	v_mfma_f32_16x16x32_bf16 v[168:171], v[250:253], v[178:181], v[90:93]
	v_mfma_f32_16x16x32_bf16 v[178:181], v[242:245], v[218:221], v[86:89]
	v_mfma_f32_16x16x32_bf16 v[214:217], v[250:253], v[218:221], v[82:85]
	v_mfma_f32_16x16x32_bf16 v[218:221], v[242:245], v[226:229], v[78:81]
	v_mfma_f32_16x16x32_bf16 v[222:225], v[250:253], v[226:229], v[74:77]
	v_mfma_f32_16x16x32_bf16 v[226:229], v[242:245], v[234:237], v[70:73]
	v_mfma_f32_16x16x32_bf16 v[230:233], v[250:253], v[234:237], v[66:69]
	s_setprio 0
	s_barrier
	s_nop 0
	ds_read_b128 v[66:69], v176 offset:16384
	ds_read_b128 v[70:73], v176 offset:17408
	ds_read_b128 v[74:77], v139 offset:18432
	ds_read_b128 v[78:81], v139 offset:19456
	ds_read_b128 v[82:85], v139 offset:20480
	ds_read_b128 v[86:89], v139 offset:21504
	ds_read_b128 v[90:93], v139 offset:22528
	ds_read_b128 v[94:97], v139 offset:23552
	s_waitcnt vmcnt(4)
	s_barrier
	s_waitcnt lgkmcnt(0)
	s_setprio 1
	s_waitcnt lgkmcnt(0)
	s_cmp_lg_u32 s101, 0
	s_cbranch_scc1 .Lg1_sk4
	v_mfma_f32_16x16x32_bf16 v[62:65], v[134:137], v[66:69], v[62:65]
	v_mfma_f32_16x16x32_bf16 v[58:61], v[160:163], v[66:69], v[58:61]
	v_mfma_f32_16x16x32_bf16 v[54:57], v[134:137], v[74:77], v[54:57]
	v_mfma_f32_16x16x32_bf16 v[50:53], v[160:163], v[74:77], v[50:53]
	v_mfma_f32_16x16x32_bf16 v[46:49], v[134:137], v[82:85], v[46:49]
	v_mfma_f32_16x16x32_bf16 v[42:45], v[160:163], v[82:85], v[42:45]
	v_mfma_f32_16x16x32_bf16 v[38:41], v[134:137], v[90:93], v[38:41]
	v_mfma_f32_16x16x32_bf16 v[34:37], v[160:163], v[90:93], v[34:37]
	v_mfma_f32_16x16x32_bf16 v[62:65], v[154:157], v[70:73], v[62:65]
	v_mfma_f32_16x16x32_bf16 v[58:61], v[164:167], v[70:73], v[58:61]
	v_mfma_f32_16x16x32_bf16 v[54:57], v[154:157], v[78:81], v[54:57]
	v_mfma_f32_16x16x32_bf16 v[50:53], v[164:167], v[78:81], v[50:53]
	v_mfma_f32_16x16x32_bf16 v[46:49], v[154:157], v[86:89], v[46:49]
	v_mfma_f32_16x16x32_bf16 v[42:45], v[164:167], v[86:89], v[42:45]
	v_mfma_f32_16x16x32_bf16 v[38:41], v[154:157], v[94:97], v[38:41]
	v_mfma_f32_16x16x32_bf16 v[34:37], v[164:167], v[94:97], v[34:37]
	s_setprio 0
	s_setprio 1
	v_mfma_f32_16x16x32_bf16 v[30:33], v[238:241], v[66:69], v[30:33]
	v_mfma_f32_16x16x32_bf16 v[26:29], v[246:249], v[66:69], v[26:29]
	v_mfma_f32_16x16x32_bf16 v[22:25], v[238:241], v[74:77], v[22:25]
	v_mfma_f32_16x16x32_bf16 v[18:21], v[246:249], v[74:77], v[18:21]
	v_mfma_f32_16x16x32_bf16 v[12:15], v[238:241], v[82:85], v[12:15]
	v_mfma_f32_16x16x32_bf16 v[8:11], v[246:249], v[82:85], v[8:11]
	v_mfma_f32_16x16x32_bf16 v[4:7], v[238:241], v[90:93], v[4:7]
	v_mfma_f32_16x16x32_bf16 v[0:3], v[246:249], v[90:93], v[0:3]
	v_mfma_f32_16x16x32_bf16 v[134:137], v[242:245], v[70:73], v[30:33]
	v_mfma_f32_16x16x32_bf16 v[154:157], v[250:253], v[70:73], v[26:29]
	v_mfma_f32_16x16x32_bf16 v[160:163], v[242:245], v[78:81], v[22:25]
	v_mfma_f32_16x16x32_bf16 v[164:167], v[250:253], v[78:81], v[18:21]
	v_mfma_f32_16x16x32_bf16 v[234:237], v[242:245], v[86:89], v[12:15]
	v_mfma_f32_16x16x32_bf16 v[82:85], v[250:253], v[86:89], v[8:11]
	v_mfma_f32_16x16x32_bf16 v[238:241], v[242:245], v[94:97], v[4:7]
	v_mfma_f32_16x16x32_bf16 v[242:245], v[250:253], v[94:97], v[0:3]
